# one static s_setprio 1 for waves 4-7 at kernel entry, all other s_setprio (peeled iterations) deleted
# baseline (speedup 1.0000x reference)
; #define LAS __attribute__((address_space(3)))
; __global__ void __launch_bounds__(NTHREADS, 2) fwd_kernel(Args args_v) {
;     ...
;     const int wave_s = __builtin_amdgcn_readfirstlane((int)threadIdx.x >> 6);
;     volatile LAS unsigned* MISC = (volatile LAS unsigned*)(ldsp + MISC_OFF);
;     for (int u = threadIdx.x; u < (LDS_BYTES - LDSCTL_OFF) / 4; u += NTHREADS) ((LAS unsigned*)(ldsp + LDSCTL_OFF))[u] = 0u;
;     __syncthreads();
;     unsigned* ctl = (unsigned*)(args_v.ws + WS_CTL);
;     const bool multi = (args_v.ph_hi - args_v.ph_lo) > 1;
;     if (multi) {
;         XcdBarrier bar = xcd_barrier_post(ctl + CW_BAR, MISC + 8);
;         if (threadIdx.x == 0) { unsigned nloc, nx; xcd_barrier_complete(ctl + CW_BAR, bar.x, nloc, nx); MISC[8] = nloc; MISC[9] = nx; }
_Z10fwd_kernel4Args:
	v_lshl_add_u32 v1, v0, 2, 0
	v_add_u32_e32 v1, 0x20000, v1
	v_mov_b32_e32 v2, 0
	v_readfirstlane_b32 s93, v0
	s_nop 3
	s_cmp_ge_u32 s93, 0x100
	s_cbranch_scc0 .Lstatic_prio_done
	s_setprio 1
.Lstatic_prio_done:
	ds_write2st64_b32 v1, v2, v2 offset1:8
	ds_write2st64_b32 v1, v2, v2 offset0:16 offset1:24
	v_or_b32_e32 v1, 0x800, v0
	s_mov_b64 s[4:5], -1
	s_and_saveexec_b64 s[6:7], s[4:5]
	v_lshl_add_u32 v3, v1, 2, 0
	v_add_u32_e32 v3, 0x20000, v3
	ds_write_b32 v3, v2
	s_or_b64 exec, exec, s[6:7]
	s_and_saveexec_b64 s[6:7], s[4:5]
	s_add_i32 s3, 0, 0x20000
	v_lshl_add_u32 v1, v1, 2, s3
	v_mov_b32_e32 v2, 0
	ds_write_b32 v1, v2 offset:2048
	s_or_b64 exec, exec, s[6:7]
	s_load_dwordx2 s[4:5], s[0:1], 0xa8
	v_or_b32_e32 v1, 0xc00, v0
	v_cmp_gt_u32_e64 s[6:7], 7, 6
	v_cmp_gt_u32_e64 s[10:11], 7, 5
	s_and_saveexec_b64 s[8:9], s[10:11]
	v_lshl_add_u32 v2, v1, 2, 0
	v_add_u32_e32 v2, 0x20000, v2
	v_mov_b32_e32 v3, 0
	ds_write_b32 v2, v3
	s_or_b64 exec, exec, s[8:9]
	s_and_saveexec_b64 s[8:9], s[6:7]
	s_add_i32 s3, 0, 0x20000
	v_lshl_add_u32 v1, v1, 2, s3
	v_mov_b32_e32 v2, 0
	ds_write_b32 v1, v2 offset:2048
	s_or_b64 exec, exec, s[8:9]
	s_waitcnt lgkmcnt(0)
	s_sub_i32 s3, s5, s4
	s_cmp_lt_i32 s3, 2
	s_barrier
	s_cbranch_scc1 .LBB0_27
	s_getreg_b32 s3, hwreg(HW_REG_XCC_ID, 0, 4)
	v_cmp_eq_u32_e32 vcc, 0, v0
	s_and_saveexec_b64 s[4:5], vcc
	s_cbranch_execz .LBB0_26
	s_load_dwordx2 s[40:41], s[0:1], 0xa0
	s_mov_b64 s[6:7], exec
	v_mbcnt_lo_u32_b32 v0, s6, 0
	v_mbcnt_hi_u32_b32 v0, s7, v0
	s_and_b32 s3, s3, 15
	v_cmp_eq_u32_e32 vcc, 0, v0
	s_and_saveexec_b64 s[8:9], vcc
	s_cbranch_execz .LBB0_12
	s_lshl_b32 s10, s3, 8
	s_waitcnt lgkmcnt(0)
	s_add_u32 s10, s40, s10
	s_addc_u32 s11, s41, 0
	s_bcnt1_i32_b64 s6, s[6:7]
	v_mov_b32_e32 v0, 0x4000
	v_mov_b32_e32 v1, s6
	global_atomic_add v0, v1, s[10:11] offset:1024

; #define PG8_LAS __attribute__((address_space(3)))
; #define PG8_STAGE(bufoff, gbase, voff) do { _Pragma("unroll") for (int _i = 0; _i < 2; ++_i) \
;         __builtin_amdgcn_global_load_lds((const unsigned*)((const char*)(gbase) + (voff)[_i]), (PG8_LAS unsigned*)(lds + (bufoff) + ldsw + _i * 8192), 16, 0, 0); } while (0)
; #define PG8_LDA(dst, b, h) do { _Pragma("unroll") for (int m = 0; m < 4; ++m) _Pragma("unroll") for (int k = 0; k < 2; ++k) dst[m][k] = *(const PG8_LAS bf16x8*)(lds + PG8_SA(b, h) + aoff + m * 2048 + k * 1024); } while (0)
; #define PG8_LDB(dst, b, h) do { _Pragma("unroll") for (int n = 0; n < 2; ++n) _Pragma("unroll") for (int k = 0; k < 2; ++k) dst[n][k] = *(const PG8_LAS bf16x8*)(lds + PG8_SB(b, h) + boff + n * 2048 + k * 1024); } while (0)
; #define PG8_WAIT_V(n) asm volatile("s_waitcnt vmcnt(" #n ")" ::: "memory")
; #define PG8_WAIT_L(n) asm volatile("s_waitcnt lgkmcnt(" #n ")" ::: "memory")
; #define PG8_BAR __builtin_amdgcn_s_barrier()
; #define PG8_SCHED __builtin_amdgcn_sched_barrier(0)
; template <class Epi, class Sched, bool ALIGN_EPI = false, bool SP2 = false>
; __device__ __forceinline__ void gemm_phase(PG8_LAS unsigned char* lds, const Gemm g, const Sched& S, const Epi& E, int wave_s) {
;     ...
;             const bool last = (t == nt - 2);
;             if constexpr (Epi::NEED_RS) { if (t == 0 && wid < 4) __builtin_amdgcn_global_load_lds((const unsigned*)(E.rstd + cur.pm * BM + wid * 64 + lane), (PG8_LAS unsigned*)(rsl + wid * 64), 4, 0, 0); }
;             const char* a1 = cA + (size_t)(t + 1) * kstep;
;             const char* a2 = last ? nA : cA + (size_t)(t + 2) * kstep; const char* b2 = last ? nB : cB + (size_t)(t + 2) * kstep;
;             const char* a3 = a2 + kstep; const char* b3 = b2 + kstep;
;             if (last && has_next) S.a_ready(nxt);
;             if constexpr (SP2) {
;             PG8_LDB(B0, 0, 0); PG8_LDB(B1, 0, 1); PG8_SCHED; PG8_LDA(At, 0, 0); PG8_STAGE(PG8_SA(1, 1), a1 + hstep, voffA);
;             PG8_WAIT_V(8); PG8_WAIT_L(0); PG8_BAR; PG8_MMA(0, 0, At, B0); PG8_MMA(0, 1, At, B1); PG8_BAR; PG8_SCHED;
;             PG8_LDA(At, 0, 1); PG8_STAGE(PG8_SB(0, 0), b2, voffB); PG8_STAGE(PG8_SB(0, 1), b2 + hstep, voffB); PG8_STAGE(PG8_SA(0, 0), a2, voffA);
;             PG8_WAIT_V(8); PG8_WAIT_L(0); PG8_BAR; PG8_MMA(1, 0, At, B0); PG8_MMA(1, 1, At, B1); PG8_BAR; PG8_SCHED;
.LBB0_40:
	s_ashr_i32 s31, s30, 31
	ds_read_b128 v[0:3], v157
	ds_read_b128 v[4:7], v157 offset:1024
	ds_read_b128 v[8:11], v157 offset:2048
	ds_read_b128 v[12:15], v157 offset:3072
	ds_read_b128 v[16:19], v158
	ds_read_b128 v[20:23], v158 offset:1024
	ds_read_b128 v[24:27], v158 offset:2048
	ds_read_b128 v[28:31], v158 offset:3072
	s_lshl_b64 s[38:39], s[30:31], 21
	s_add_u32 s38, s52, s38
	s_addc_u32 s39, s53, s39
	s_and_b64 s[40:41], s[36:37], exec
	s_cselect_b32 s31, s39, s47
	s_cselect_b32 s72, s38, s46
	s_ashr_i32 s35, s34, 31
	s_lshl_b64 s[40:41], s[34:35], 21
	s_add_u32 s40, s54, s40
	s_addc_u32 s41, s55, s41
	s_and_b64 s[50:51], s[36:37], exec
	s_cselect_b32 s35, s41, s49
	s_cselect_b32 s73, s40, s48
	s_add_u32 s50, s46, 0x100080
	s_addc_u32 s51, s47, 0
	s_add_i32 s74, s43, 0xc000
	v_lshl_add_u64 v[64:65], s[50:51], 0, v[134:135]
	s_mov_b32 m0, s74
	s_add_i32 s75, s43, 0xe000
	ds_read_b128 v[32:35], v159
	ds_read_b128 v[36:39], v159 offset:1024
	ds_read_b128 v[40:43], v159 offset:2048
	ds_read_b128 v[44:47], v159 offset:3072
	ds_read_b128 v[48:51], v159 offset:4096
	ds_read_b128 v[52:55], v159 offset:5120
	ds_read_b128 v[56:59], v159 offset:6144
	ds_read_b128 v[60:63], v159 offset:7168
	global_load_lds_dwordx4 v[64:65], off
	v_lshl_add_u64 v[64:65], s[50:51], 0, v[130:131]
	s_mov_b32 m0, s75
	s_nop 0
	global_load_lds_dwordx4 v[64:65], off
	s_waitcnt vmcnt(8)
	s_waitcnt lgkmcnt(0)
	s_barrier
	s_waitcnt lgkmcnt(0)
	v_mfma_f32_16x16x32_bf16 v[88:91], v[0:3], v[56:59], 0
	v_mfma_f32_16x16x32_bf16 v[64:67], v[0:3], v[32:35], 0
	v_mfma_f32_16x16x32_bf16 v[68:71], v[8:11], v[32:35], 0
	v_mfma_f32_16x16x32_bf16 v[72:75], v[0:3], v[40:43], 0
	v_mfma_f32_16x16x32_bf16 v[76:79], v[8:11], v[40:43], 0
	v_mfma_f32_16x16x32_bf16 v[80:83], v[0:3], v[48:51], 0
	v_mfma_f32_16x16x32_bf16 v[84:87], v[8:11], v[48:51], 0
	v_mfma_f32_16x16x32_bf16 v[96:99], v[4:7], v[60:63], v[88:91]
	v_mfma_f32_16x16x32_bf16 v[88:91], v[8:11], v[56:59], 0
	v_mfma_f32_16x16x32_bf16 v[64:67], v[4:7], v[36:39], v[64:67]
	v_mfma_f32_16x16x32_bf16 v[68:71], v[12:15], v[36:39], v[68:71]
	v_mfma_f32_16x16x32_bf16 v[72:75], v[4:7], v[44:47], v[72:75]
	v_mfma_f32_16x16x32_bf16 v[76:79], v[12:15], v[44:47], v[76:79]
	v_mfma_f32_16x16x32_bf16 v[80:83], v[4:7], v[52:55], v[80:83]
	v_mfma_f32_16x16x32_bf16 v[84:87], v[12:15], v[52:55], v[84:87]
	v_mfma_f32_16x16x32_bf16 v[100:103], v[12:15], v[60:63], v[88:91]
	v_mfma_f32_16x16x32_bf16 v[88:91], v[16:19], v[32:35], 0
	v_mfma_f32_16x16x32_bf16 v[32:35], v[24:27], v[32:35], 0
	v_mfma_f32_16x16x32_bf16 v[112:115], v[20:23], v[36:39], v[88:91]
	v_mfma_f32_16x16x32_bf16 v[32:35], v[28:31], v[36:39], v[32:35]
	v_mfma_f32_16x16x32_bf16 v[36:39], v[16:19], v[40:43], 0
	v_mfma_f32_16x16x32_bf16 v[40:43], v[24:27], v[40:43], 0
	v_mfma_f32_16x16x32_bf16 v[36:39], v[20:23], v[44:47], v[36:39]
	v_mfma_f32_16x16x32_bf16 v[40:43], v[28:31], v[44:47], v[40:43]
	v_mfma_f32_16x16x32_bf16 v[44:47], v[16:19], v[48:51], 0
	v_mfma_f32_16x16x32_bf16 v[48:51], v[24:27], v[48:51], 0
	v_mfma_f32_16x16x32_bf16 v[44:47], v[20:23], v[52:55], v[44:47]
	v_mfma_f32_16x16x32_bf16 v[48:51], v[28:31], v[52:55], v[48:51]
	v_mfma_f32_16x16x32_bf16 v[52:55], v[16:19], v[56:59], 0
	v_mfma_f32_16x16x32_bf16 v[56:59], v[24:27], v[56:59], 0
	v_mfma_f32_16x16x32_bf16 v[52:55], v[20:23], v[60:63], v[52:55]
	v_mfma_f32_16x16x32_bf16 v[60:63], v[28:31], v[60:63], v[56:59]
	s_barrier
	s_add_i32 s76, s67, s56
	v_lshl_add_u64 v[244:245], s[48:49], 0, v[132:133]
	s_add_i32 s77, s76, 0x2000
	v_lshl_add_u64 v[142:143], v[244:245], 0, s[18:19]
	s_mov_b32 m0, s76
	v_lshl_add_u64 v[246:247], s[48:49], 0, v[128:129]
	s_add_u32 s50, s48, 0x100100
	ds_read_b128 v[56:59], v159 offset:16384
	ds_read_b128 v[88:91], v159 offset:17408
	ds_read_b128 v[92:95], v159 offset:18432
	ds_read_b128 v[104:107], v159 offset:19456
	ds_read_b128 v[108:111], v159 offset:20480
	ds_read_b128 v[116:119], v159 offset:21504
	ds_read_b128 v[120:123], v159 offset:22528
	ds_read_b128 v[124:127], v159 offset:23552
	global_load_lds_dwordx4 v[142:143], off
	v_lshl_add_u64 v[142:143], v[246:247], 0, s[18:19]
	s_mov_b32 m0, s77
	s_addc_u32 s51, s49, 0
	s_add_i32 s78, s69, s56
	global_load_lds_dwordx4 v[142:143], off
	v_lshl_add_u64 v[142:143], s[50:51], 0, v[132:133]
	s_mov_b32 m0, s78
	s_add_i32 s79, s78, 0x2000
	global_load_lds_dwordx4 v[142:143], off
	v_lshl_add_u64 v[142:143], s[50:51], 0, v[128:129]
	s_mov_b32 m0, s79
	v_lshl_add_u64 v[248:249], s[46:47], 0, v[134:135]
	global_load_lds_dwordx4 v[142:143], off
	v_lshl_add_u64 v[142:143], v[248:249], 0, s[18:19]
	s_mov_b32 m0, s43
	v_lshl_add_u64 v[250:251], s[46:47], 0, v[130:131]
	global_load_lds_dwordx4 v[142:143], off
	v_lshl_add_u64 v[142:143], v[250:251], 0, s[18:19]
	s_mov_b32 m0, s57
	s_nop 0
	global_load_lds_dwordx4 v[142:143], off
	s_waitcnt vmcnt(8)
	s_waitcnt lgkmcnt(0)
	s_barrier
; #define PG8_STAGE(bufoff, gbase, voff) do { _Pragma("unroll") for (int _i = 0; _i < 2; ++_i) \
;         __builtin_amdgcn_global_load_lds((const unsigned*)((const char*)(gbase) + (voff)[_i]), (PG8_LAS unsigned*)(lds + (bufoff) + ldsw + _i * 8192), 16, 0, 0); } while (0)
; #define PG8_LDA(dst, b, h) do { _Pragma("unroll") for (int m = 0; m < 4; ++m) _Pragma("unroll") for (int k = 0; k < 2; ++k) dst[m][k] = *(const PG8_LAS bf16x8*)(lds + PG8_SA(b, h) + aoff + m * 2048 + k * 1024); } while (0)
; #define PG8_LDB(dst, b, h) do { _Pragma("unroll") for (int n = 0; n < 2; ++n) _Pragma("unroll") for (int k = 0; k < 2; ++k) dst[n][k] = *(const PG8_LAS bf16x8*)(lds + PG8_SB(b, h) + boff + n * 2048 + k * 1024); } while (0)
; #define PG8_MMA(ai, bj, At, Bt) do { __builtin_amdgcn_s_setprio(1); _Pragma("unroll") for (int m = 0; m < 4; ++m) _Pragma("unroll") for (int n = 0; n < 2; ++n) _Pragma("unroll") for (int k = 0; k < 2; ++k) \
;         acc[ai][bj][m][n] = __builtin_amdgcn_mfma_f32_16x16x32_bf16(Bt[n][k], At[m][k], acc[ai][bj][m][n], 0, 0, 0); __builtin_amdgcn_s_setprio(0); } while (0)
; #define PG8_WAIT_V(n) asm volatile("s_waitcnt vmcnt(" #n ")" ::: "memory")
; #define PG8_WAIT_L(n) asm volatile("s_waitcnt lgkmcnt(" #n ")" ::: "memory")
; #define PG8_BAR __builtin_amdgcn_s_barrier()
; #define PG8_SCHED __builtin_amdgcn_sched_barrier(0)
; template <class Epi, class Sched, bool ALIGN_EPI = false, bool SP2 = false>
; __device__ __forceinline__ void gemm_phase(PG8_LAS unsigned char* lds, const Gemm g, const Sched& S, const Epi& E, int wave_s) {
;     ...
;             PG8_WAIT_V(8); PG8_WAIT_L(0); PG8_BAR; PG8_MMA(1, 0, At, B0); PG8_MMA(1, 1, At, B1); PG8_BAR; PG8_SCHED;
;             PG8_LDB(B0, 1, 0); PG8_LDB(B1, 1, 1); PG8_SCHED; PG8_LDA(At, 1, 0); PG8_STAGE(PG8_SA(0, 1), a2 + hstep, voffA);
;             PG8_WAIT_V(8); PG8_WAIT_L(0); PG8_BAR; PG8_MMA(0, 0, At, B0); PG8_MMA(0, 1, At, B1); PG8_BAR; PG8_SCHED;
	s_waitcnt lgkmcnt(0)
	v_mfma_f32_16x16x32_bf16 v[142:145], v[0:3], v[56:59], 0
	v_mfma_f32_16x16x32_bf16 v[152:155], v[0:3], v[92:95], 0
	v_mfma_f32_16x16x32_bf16 v[164:167], v[0:3], v[108:111], 0
	v_mfma_f32_16x16x32_bf16 v[0:3], v[0:3], v[120:123], 0
	v_mfma_f32_16x16x32_bf16 v[144:147], v[4:7], v[88:91], v[142:145]
	v_mfma_f32_16x16x32_bf16 v[152:155], v[4:7], v[104:107], v[152:155]
	v_mfma_f32_16x16x32_bf16 v[164:167], v[4:7], v[116:119], v[164:167]
	v_mfma_f32_16x16x32_bf16 v[0:3], v[4:7], v[124:127], v[0:3]
	v_mfma_f32_16x16x32_bf16 v[4:7], v[8:11], v[120:123], 0
	v_mfma_f32_16x16x32_bf16 v[148:151], v[8:11], v[56:59], 0
	v_mfma_f32_16x16x32_bf16 v[160:163], v[8:11], v[92:95], 0
	v_mfma_f32_16x16x32_bf16 v[168:171], v[8:11], v[108:111], 0
	v_mfma_f32_16x16x32_bf16 v[4:7], v[12:15], v[124:127], v[4:7]
	v_mfma_f32_16x16x32_bf16 v[148:151], v[12:15], v[88:91], v[148:151]
	v_mfma_f32_16x16x32_bf16 v[160:163], v[12:15], v[104:107], v[160:163]
	v_mfma_f32_16x16x32_bf16 v[168:171], v[12:15], v[116:119], v[168:171]
	v_mfma_f32_16x16x32_bf16 v[8:11], v[16:19], v[56:59], 0
	v_mfma_f32_16x16x32_bf16 v[172:175], v[20:23], v[88:91], v[8:11]
	v_mfma_f32_16x16x32_bf16 v[8:11], v[24:27], v[56:59], 0
	v_mfma_f32_16x16x32_bf16 v[176:179], v[28:31], v[88:91], v[8:11]
	v_mfma_f32_16x16x32_bf16 v[8:11], v[16:19], v[92:95], 0
	v_mfma_f32_16x16x32_bf16 v[180:183], v[20:23], v[104:107], v[8:11]
	v_mfma_f32_16x16x32_bf16 v[8:11], v[24:27], v[92:95], 0
	v_mfma_f32_16x16x32_bf16 v[184:187], v[28:31], v[104:107], v[8:11]
	v_mfma_f32_16x16x32_bf16 v[8:11], v[16:19], v[108:111], 0
	v_mfma_f32_16x16x32_bf16 v[188:191], v[20:23], v[116:119], v[8:11]
	v_mfma_f32_16x16x32_bf16 v[8:11], v[24:27], v[108:111], 0
	v_mfma_f32_16x16x32_bf16 v[192:195], v[28:31], v[116:119], v[8:11]
	v_mfma_f32_16x16x32_bf16 v[8:11], v[16:19], v[120:123], 0
	v_mfma_f32_16x16x32_bf16 v[196:199], v[20:23], v[124:127], v[8:11]
	v_mfma_f32_16x16x32_bf16 v[8:11], v[24:27], v[120:123], 0
	v_mfma_f32_16x16x32_bf16 v[200:203], v[28:31], v[124:127], v[8:11]
	s_barrier
	s_add_i32 s80, 0, 0x18000
	s_add_i32 s82, 0, 0x1c000
	v_add_u32_e32 v142, s80, v156
	v_add_u32_e32 v143, s82, v156
	s_nop 0
	ds_read_b128 v[8:11], v142
	ds_read_b128 v[12:15], v142 offset:1024
	ds_read_b128 v[16:19], v142 offset:2048
	ds_read_b128 v[20:23], v142 offset:3072
	ds_read_b128 v[204:207], v143
	ds_read_b128 v[208:211], v143 offset:1024
	ds_read_b128 v[212:215], v143 offset:2048
	ds_read_b128 v[216:219], v143 offset:3072
	s_add_u32 s50, s46, 0x100100
	s_addc_u32 s51, s47, 0
	s_mov_b32 m0, s58
	v_lshl_add_u64 v[56:57], s[50:51], 0, v[134:135]
	ds_read_b128 v[24:27], v159 offset:32768
	ds_read_b128 v[28:31], v159 offset:33792
	ds_read_b128 v[220:223], v159 offset:34816
	ds_read_b128 v[224:227], v159 offset:35840
	ds_read_b128 v[228:231], v159 offset:36864
	ds_read_b128 v[232:235], v159 offset:37888
	ds_read_b128 v[236:239], v159 offset:38912
	ds_read_b128 v[240:243], v159 offset:39936
	global_load_lds_dwordx4 v[56:57], off
	v_lshl_add_u64 v[56:57], s[50:51], 0, v[130:131]
	s_mov_b32 m0, s59
	s_nop 0
	global_load_lds_dwordx4 v[56:57], off
	s_waitcnt vmcnt(8)
	s_waitcnt lgkmcnt(0)
	s_barrier
	s_waitcnt lgkmcnt(0)
	v_mfma_f32_16x16x32_bf16 v[56:59], v[8:11], v[24:27], v[64:67]
	v_mfma_f32_16x16x32_bf16 v[124:127], v[12:15], v[28:31], v[56:59]
	v_mfma_f32_16x16x32_bf16 v[56:59], v[16:19], v[24:27], v[68:71]
	v_mfma_f32_16x16x32_bf16 v[120:123], v[20:23], v[28:31], v[56:59]
	v_mfma_f32_16x16x32_bf16 v[56:59], v[8:11], v[220:223], v[72:75]
	v_mfma_f32_16x16x32_bf16 v[108:111], v[12:15], v[224:227], v[56:59]
	v_mfma_f32_16x16x32_bf16 v[56:59], v[16:19], v[220:223], v[76:79]
	v_mfma_f32_16x16x32_bf16 v[104:107], v[20:23], v[224:227], v[56:59]
	v_mfma_f32_16x16x32_bf16 v[56:59], v[8:11], v[228:231], v[80:83]
	v_mfma_f32_16x16x32_bf16 v[92:95], v[12:15], v[232:235], v[56:59]
	v_mfma_f32_16x16x32_bf16 v[56:59], v[16:19], v[228:231], v[84:87]
	v_mfma_f32_16x16x32_bf16 v[88:91], v[20:23], v[232:235], v[56:59]
	v_mfma_f32_16x16x32_bf16 v[56:59], v[8:11], v[236:239], v[96:99]
	v_mfma_f32_16x16x32_bf16 v[64:67], v[12:15], v[240:243], v[56:59]
	v_mfma_f32_16x16x32_bf16 v[56:59], v[16:19], v[236:239], v[100:103]
	v_mfma_f32_16x16x32_bf16 v[56:59], v[20:23], v[240:243], v[56:59]
	v_mfma_f32_16x16x32_bf16 v[68:71], v[204:207], v[24:27], v[112:115]
	v_mfma_f32_16x16x32_bf16 v[24:27], v[212:215], v[24:27], v[32:35]
	v_mfma_f32_16x16x32_bf16 v[112:115], v[216:219], v[28:31], v[24:27]
	v_mfma_f32_16x16x32_bf16 v[24:27], v[204:207], v[220:223], v[36:39]
	v_mfma_f32_16x16x32_bf16 v[100:103], v[208:211], v[224:227], v[24:27]
	v_mfma_f32_16x16x32_bf16 v[24:27], v[212:215], v[220:223], v[40:43]
	v_mfma_f32_16x16x32_bf16 v[96:99], v[216:219], v[224:227], v[24:27]
	v_mfma_f32_16x16x32_bf16 v[24:27], v[204:207], v[228:231], v[44:47]
	v_mfma_f32_16x16x32_bf16 v[84:87], v[208:211], v[232:235], v[24:27]
	v_mfma_f32_16x16x32_bf16 v[24:27], v[212:215], v[228:231], v[48:51]
	v_mfma_f32_16x16x32_bf16 v[80:83], v[216:219], v[232:235], v[24:27]
	v_mfma_f32_16x16x32_bf16 v[24:27], v[204:207], v[236:239], v[52:55]
	v_mfma_f32_16x16x32_bf16 v[52:55], v[208:211], v[240:243], v[24:27]
	v_mfma_f32_16x16x32_bf16 v[24:27], v[212:215], v[236:239], v[60:63]
	v_mfma_f32_16x16x32_bf16 v[116:119], v[208:211], v[28:31], v[68:71]
	v_mfma_f32_16x16x32_bf16 v[48:51], v[216:219], v[240:243], v[24:27]
	s_barrier
; #define PG8_STAGE(bufoff, gbase, voff) do { _Pragma("unroll") for (int _i = 0; _i < 2; ++_i) \
;         __builtin_amdgcn_global_load_lds((const unsigned*)((const char*)(gbase) + (voff)[_i]), (PG8_LAS unsigned*)(lds + (bufoff) + ldsw + _i * 8192), 16, 0, 0); } while (0)
; #define PG8_LDA(dst, b, h) do { _Pragma("unroll") for (int m = 0; m < 4; ++m) _Pragma("unroll") for (int k = 0; k < 2; ++k) dst[m][k] = *(const PG8_LAS bf16x8*)(lds + PG8_SA(b, h) + aoff + m * 2048 + k * 1024); } while (0)
; #define PG8_MMA(ai, bj, At, Bt) do { __builtin_amdgcn_s_setprio(1); _Pragma("unroll") for (int m = 0; m < 4; ++m) _Pragma("unroll") for (int n = 0; n < 2; ++n) _Pragma("unroll") for (int k = 0; k < 2; ++k) \
;         acc[ai][bj][m][n] = __builtin_amdgcn_mfma_f32_16x16x32_bf16(Bt[n][k], At[m][k], acc[ai][bj][m][n], 0, 0, 0); __builtin_amdgcn_s_setprio(0); } while (0)
; #define PG8_WAIT_V(n) asm volatile("s_waitcnt vmcnt(" #n ")" ::: "memory")
; #define PG8_WAIT_L(n) asm volatile("s_waitcnt lgkmcnt(" #n ")" ::: "memory")
; #define PG8_BAR __builtin_amdgcn_s_barrier()
; #define PG8_SCHED __builtin_amdgcn_sched_barrier(0)
; template <class Epi, class Sched, bool ALIGN_EPI = false, bool SP2 = false>
; __device__ __forceinline__ void gemm_phase(PG8_LAS unsigned char* lds, const Gemm g, const Sched& S, const Epi& E, int wave_s) {
;     ...
;             PG8_LDA(At, 1, 1); PG8_STAGE(PG8_SB(1, 0), b3, voffB); PG8_STAGE(PG8_SB(1, 1), b3 + hstep, voffB); PG8_STAGE(PG8_SA(1, 0), a3, voffA);
;             PG8_WAIT_V(8); PG8_WAIT_L(0); PG8_BAR; PG8_MMA(1, 0, At, B0); PG8_MMA(1, 1, At, B1); PG8_BAR; PG8_SCHED;
	s_add_i32 s80, s80, s56
	s_add_i32 s81, s80, 0x2000
	s_nop 1
	v_lshl_add_u64 v[24:25], v[244:245], 0, s[20:21]
	s_mov_b32 m0, s80
	s_add_u32 s50, s48, 0x100180
	ds_read_b128 v[32:35], v159 offset:49152
	ds_read_b128 v[36:39], v159 offset:50176
	ds_read_b128 v[220:223], v159 offset:51200
	ds_read_b128 v[224:227], v159 offset:52224
	ds_read_b128 v[228:231], v159 offset:53248
	ds_read_b128 v[232:235], v159 offset:54272
	ds_read_b128 v[236:239], v159 offset:55296
	ds_read_b128 v[240:243], v159 offset:56320
	global_load_lds_dwordx4 v[24:25], off
	v_lshl_add_u64 v[24:25], v[246:247], 0, s[20:21]
	s_mov_b32 m0, s81
	s_addc_u32 s51, s49, 0
	s_add_i32 s82, s82, s56
	global_load_lds_dwordx4 v[24:25], off
	v_lshl_add_u64 v[24:25], s[50:51], 0, v[132:133]
	s_mov_b32 m0, s82
	s_add_i32 s83, s82, 0x2000
	global_load_lds_dwordx4 v[24:25], off
	v_lshl_add_u64 v[24:25], s[50:51], 0, v[128:129]
	s_mov_b32 m0, s83
	s_nop 0
	global_load_lds_dwordx4 v[24:25], off
	v_lshl_add_u64 v[24:25], v[248:249], 0, s[20:21]
	s_mov_b32 m0, s64
	s_nop 0
	global_load_lds_dwordx4 v[24:25], off
	v_lshl_add_u64 v[24:25], v[250:251], 0, s[20:21]
	s_mov_b32 m0, s65
	s_nop 0
	global_load_lds_dwordx4 v[24:25], off
	s_waitcnt vmcnt(8)
	s_waitcnt lgkmcnt(0)
	s_barrier
	s_waitcnt lgkmcnt(0)
	v_mfma_f32_16x16x32_bf16 v[24:27], v[8:11], v[32:35], v[144:147]
	v_mfma_f32_16x16x32_bf16 v[76:79], v[12:15], v[36:39], v[24:27]
	v_mfma_f32_16x16x32_bf16 v[24:27], v[16:19], v[32:35], v[148:151]
	v_mfma_f32_16x16x32_bf16 v[72:75], v[20:23], v[36:39], v[24:27]
	v_mfma_f32_16x16x32_bf16 v[24:27], v[8:11], v[220:223], v[152:155]
	v_mfma_f32_16x16x32_bf16 v[44:47], v[12:15], v[224:227], v[24:27]
	v_mfma_f32_16x16x32_bf16 v[24:27], v[16:19], v[220:223], v[160:163]
	v_mfma_f32_16x16x32_bf16 v[40:43], v[20:23], v[224:227], v[24:27]
	v_mfma_f32_16x16x32_bf16 v[24:27], v[8:11], v[228:231], v[164:167]
	v_mfma_f32_16x16x32_bf16 v[0:3], v[8:11], v[236:239], v[0:3]
	v_mfma_f32_16x16x32_bf16 v[28:31], v[12:15], v[232:235], v[24:27]
	v_mfma_f32_16x16x32_bf16 v[24:27], v[16:19], v[228:231], v[168:171]
	v_mfma_f32_16x16x32_bf16 v[12:15], v[12:15], v[240:243], v[0:3]
	v_mfma_f32_16x16x32_bf16 v[0:3], v[16:19], v[236:239], v[4:7]
	v_mfma_f32_16x16x32_bf16 v[24:27], v[20:23], v[232:235], v[24:27]
	v_mfma_f32_16x16x32_bf16 v[8:11], v[20:23], v[240:243], v[0:3]
	v_mfma_f32_16x16x32_bf16 v[0:3], v[204:207], v[32:35], v[172:175]
	v_mfma_f32_16x16x32_bf16 v[68:71], v[208:211], v[36:39], v[0:3]
	v_mfma_f32_16x16x32_bf16 v[0:3], v[212:215], v[32:35], v[176:179]
	v_mfma_f32_16x16x32_bf16 v[60:63], v[216:219], v[36:39], v[0:3]
	v_mfma_f32_16x16x32_bf16 v[0:3], v[204:207], v[220:223], v[180:183]
	v_mfma_f32_16x16x32_bf16 v[36:39], v[208:211], v[224:227], v[0:3]
	v_mfma_f32_16x16x32_bf16 v[0:3], v[212:215], v[220:223], v[184:187]
	v_mfma_f32_16x16x32_bf16 v[32:35], v[216:219], v[224:227], v[0:3]
	v_mfma_f32_16x16x32_bf16 v[0:3], v[204:207], v[228:231], v[188:191]
	v_mfma_f32_16x16x32_bf16 v[20:23], v[208:211], v[232:235], v[0:3]
	v_mfma_f32_16x16x32_bf16 v[0:3], v[212:215], v[228:231], v[192:195]
	v_mfma_f32_16x16x32_bf16 v[16:19], v[216:219], v[232:235], v[0:3]
	v_mfma_f32_16x16x32_bf16 v[0:3], v[204:207], v[236:239], v[196:199]
	v_mfma_f32_16x16x32_bf16 v[4:7], v[208:211], v[240:243], v[0:3]
	v_mfma_f32_16x16x32_bf16 v[0:3], v[212:215], v[236:239], v[200:203]
	v_mfma_f32_16x16x32_bf16 v[0:3], v[216:219], v[240:243], v[0:3]
	s_barrier
	s_add_u32 s46, s46, 0x100180
	s_addc_u32 s47, s47, 0
	s_add_u32 s84, s48, 0x200
	s_addc_u32 s85, s49, 0
	s_mov_b32 s86, 0

; #define PG8_LAS __attribute__((address_space(3)))
; #define PG8_STAGE(bufoff, gbase, voff) do { _Pragma("unroll") for (int _i = 0; _i < 2; ++_i) \
;         __builtin_amdgcn_global_load_lds((const unsigned*)((const char*)(gbase) + (voff)[_i]), (PG8_LAS unsigned*)(lds + (bufoff) + ldsw + _i * 8192), 16, 0, 0); } while (0)
; #define PG8_LDA(dst, b, h) do { _Pragma("unroll") for (int m = 0; m < 4; ++m) _Pragma("unroll") for (int k = 0; k < 2; ++k) dst[m][k] = *(const PG8_LAS bf16x8*)(lds + PG8_SA(b, h) + aoff + m * 2048 + k * 1024); } while (0)
; #define PG8_LDB(dst, b, h) do { _Pragma("unroll") for (int n = 0; n < 2; ++n) _Pragma("unroll") for (int k = 0; k < 2; ++k) dst[n][k] = *(const PG8_LAS bf16x8*)(lds + PG8_SB(b, h) + boff + n * 2048 + k * 1024); } while (0)
; #define PG8_WAIT_V(n) asm volatile("s_waitcnt vmcnt(" #n ")" ::: "memory")
; #define PG8_WAIT_L(n) asm volatile("s_waitcnt lgkmcnt(" #n ")" ::: "memory")
; #define PG8_BAR __builtin_amdgcn_s_barrier()
; #define PG8_SCHED __builtin_amdgcn_sched_barrier(0)
; template <class Epi, class Sched, bool ALIGN_EPI = false, bool SP2 = false>
; __device__ __forceinline__ void gemm_phase(PG8_LAS unsigned char* lds, const Gemm g, const Sched& S, const Epi& E, int wave_s) {
;     ...
;             const bool last = (t == nt - 2);
;             if constexpr (Epi::NEED_RS) { if (t == 0 && wid < 4) __builtin_amdgcn_global_load_lds((const unsigned*)(E.rstd + cur.pm * BM + wid * 64 + lane), (PG8_LAS unsigned*)(rsl + wid * 64), 4, 0, 0); }
;             const char* a1 = cA + (size_t)(t + 1) * kstep;
;             const char* a2 = last ? nA : cA + (size_t)(t + 2) * kstep; const char* b2 = last ? nB : cB + (size_t)(t + 2) * kstep;
;             const char* a3 = a2 + kstep; const char* b3 = b2 + kstep;
;             if (last && has_next) S.a_ready(nxt);
;             if constexpr (SP2) {
;             PG8_LDB(B0, 0, 0); PG8_LDB(B1, 0, 1); PG8_SCHED; PG8_LDA(At, 0, 0); PG8_STAGE(PG8_SA(1, 1), a1 + hstep, voffA);
;             PG8_WAIT_V(8); PG8_WAIT_L(0); PG8_BAR; PG8_MMA(0, 0, At, B0); PG8_MMA(0, 1, At, B1); PG8_BAR; PG8_SCHED;
;             PG8_LDA(At, 0, 1); PG8_STAGE(PG8_SB(0, 0), b2, voffB); PG8_STAGE(PG8_SB(0, 1), b2 + hstep, voffB); PG8_STAGE(PG8_SA(0, 0), a2, voffA);
;             PG8_WAIT_V(8); PG8_WAIT_L(0); PG8_BAR; PG8_MMA(1, 0, At, B0); PG8_MMA(1, 1, At, B1); PG8_BAR; PG8_SCHED;
.LBB0_1342:
	s_ashr_i32 s29, s28, 31
	ds_read_b128 v[0:3], v149
	ds_read_b128 v[4:7], v149 offset:1024
	ds_read_b128 v[8:11], v149 offset:2048
	ds_read_b128 v[12:15], v149 offset:3072
	ds_read_b128 v[16:19], v150
	ds_read_b128 v[20:23], v150 offset:1024
	ds_read_b128 v[24:27], v150 offset:2048
	ds_read_b128 v[28:31], v150 offset:3072
	s_lshl_b64 s[36:37], s[28:29], 21
	s_add_u32 s36, s53, s36
	s_addc_u32 s37, s54, s37
	s_and_b64 s[38:39], s[30:31], exec
	s_cselect_b32 s29, s37, s45
	s_cselect_b32 s74, s36, s44
	s_ashr_i32 s35, s34, 31
	s_lshl_b64 s[38:39], s[34:35], 21
	s_add_u32 s38, s55, s38
	s_addc_u32 s39, s56, s39
	s_and_b64 s[48:49], s[30:31], exec
	s_cselect_b32 s35, s39, s47
	s_cselect_b32 s75, s38, s46
	s_add_u32 s48, s44, 0x100080
	s_addc_u32 s49, s45, 0
	s_add_i32 s76, s41, 0xc000
	v_lshl_add_u64 v[64:65], s[48:49], 0, v[134:135]
	s_mov_b32 m0, s76
	s_add_i32 s77, s41, 0xe000
	ds_read_b128 v[32:35], v151
	ds_read_b128 v[36:39], v151 offset:1024
	ds_read_b128 v[40:43], v151 offset:2048
	ds_read_b128 v[44:47], v151 offset:3072
	ds_read_b128 v[48:51], v151 offset:4096
	ds_read_b128 v[52:55], v151 offset:5120
	ds_read_b128 v[56:59], v151 offset:6144
	ds_read_b128 v[60:63], v151 offset:7168
	global_load_lds_dwordx4 v[64:65], off
	v_lshl_add_u64 v[64:65], s[48:49], 0, v[130:131]
	s_mov_b32 m0, s77
	s_nop 0
	global_load_lds_dwordx4 v[64:65], off
	s_waitcnt vmcnt(8)
	s_waitcnt lgkmcnt(0)
	s_barrier
	s_waitcnt lgkmcnt(0)
	v_mfma_f32_16x16x32_bf16 v[88:91], v[0:3], v[56:59], 0
	v_mfma_f32_16x16x32_bf16 v[64:67], v[0:3], v[32:35], 0
	v_mfma_f32_16x16x32_bf16 v[68:71], v[8:11], v[32:35], 0
	v_mfma_f32_16x16x32_bf16 v[72:75], v[0:3], v[40:43], 0
	v_mfma_f32_16x16x32_bf16 v[76:79], v[8:11], v[40:43], 0
	v_mfma_f32_16x16x32_bf16 v[80:83], v[0:3], v[48:51], 0
	v_mfma_f32_16x16x32_bf16 v[84:87], v[8:11], v[48:51], 0
	v_mfma_f32_16x16x32_bf16 v[96:99], v[4:7], v[60:63], v[88:91]
	v_mfma_f32_16x16x32_bf16 v[88:91], v[8:11], v[56:59], 0
	v_mfma_f32_16x16x32_bf16 v[64:67], v[4:7], v[36:39], v[64:67]
	v_mfma_f32_16x16x32_bf16 v[68:71], v[12:15], v[36:39], v[68:71]
	v_mfma_f32_16x16x32_bf16 v[72:75], v[4:7], v[44:47], v[72:75]
	v_mfma_f32_16x16x32_bf16 v[76:79], v[12:15], v[44:47], v[76:79]
	v_mfma_f32_16x16x32_bf16 v[80:83], v[4:7], v[52:55], v[80:83]
	v_mfma_f32_16x16x32_bf16 v[84:87], v[12:15], v[52:55], v[84:87]
	v_mfma_f32_16x16x32_bf16 v[100:103], v[12:15], v[60:63], v[88:91]
	v_mfma_f32_16x16x32_bf16 v[88:91], v[16:19], v[32:35], 0
	v_mfma_f32_16x16x32_bf16 v[32:35], v[24:27], v[32:35], 0
	v_mfma_f32_16x16x32_bf16 v[112:115], v[20:23], v[36:39], v[88:91]
	v_mfma_f32_16x16x32_bf16 v[32:35], v[28:31], v[36:39], v[32:35]
	v_mfma_f32_16x16x32_bf16 v[36:39], v[16:19], v[40:43], 0
	v_mfma_f32_16x16x32_bf16 v[40:43], v[24:27], v[40:43], 0
	v_mfma_f32_16x16x32_bf16 v[36:39], v[20:23], v[44:47], v[36:39]
	v_mfma_f32_16x16x32_bf16 v[40:43], v[28:31], v[44:47], v[40:43]
	v_mfma_f32_16x16x32_bf16 v[44:47], v[16:19], v[48:51], 0
	v_mfma_f32_16x16x32_bf16 v[48:51], v[24:27], v[48:51], 0
	v_mfma_f32_16x16x32_bf16 v[44:47], v[20:23], v[52:55], v[44:47]
	v_mfma_f32_16x16x32_bf16 v[48:51], v[28:31], v[52:55], v[48:51]
	v_mfma_f32_16x16x32_bf16 v[52:55], v[16:19], v[56:59], 0
	v_mfma_f32_16x16x32_bf16 v[56:59], v[24:27], v[56:59], 0
	v_mfma_f32_16x16x32_bf16 v[52:55], v[20:23], v[60:63], v[52:55]
	v_mfma_f32_16x16x32_bf16 v[56:59], v[28:31], v[60:63], v[56:59]
	s_barrier
	s_add_i32 s78, s65, s57
	v_lshl_add_u64 v[244:245], s[46:47], 0, v[132:133]
	s_add_i32 s79, s78, 0x2000
	v_lshl_add_u64 v[142:143], v[244:245], 0, s[16:17]
	s_mov_b32 m0, s78
	v_lshl_add_u64 v[246:247], s[46:47], 0, v[128:129]
	s_add_u32 s48, s46, 0x100100
	ds_read_b128 v[60:63], v151 offset:16384
	ds_read_b128 v[88:91], v151 offset:17408
	ds_read_b128 v[92:95], v151 offset:18432
	ds_read_b128 v[104:107], v151 offset:19456
	ds_read_b128 v[108:111], v151 offset:20480
	ds_read_b128 v[116:119], v151 offset:21504
	ds_read_b128 v[120:123], v151 offset:22528
	ds_read_b128 v[124:127], v151 offset:23552
	global_load_lds_dwordx4 v[142:143], off
	v_lshl_add_u64 v[142:143], v[246:247], 0, s[16:17]
	s_mov_b32 m0, s79
	s_addc_u32 s49, s47, 0
	s_add_i32 s80, s66, s57
	global_load_lds_dwordx4 v[142:143], off
	v_lshl_add_u64 v[142:143], s[48:49], 0, v[132:133]
	s_mov_b32 m0, s80
	s_add_i32 s81, s80, 0x2000
	global_load_lds_dwordx4 v[142:143], off
	v_lshl_add_u64 v[142:143], s[48:49], 0, v[128:129]
	s_mov_b32 m0, s81
	v_lshl_add_u64 v[248:249], s[44:45], 0, v[134:135]
	global_load_lds_dwordx4 v[142:143], off
	v_lshl_add_u64 v[142:143], v[248:249], 0, s[16:17]
	s_mov_b32 m0, s41
	v_lshl_add_u64 v[250:251], s[44:45], 0, v[130:131]
	global_load_lds_dwordx4 v[142:143], off
	v_lshl_add_u64 v[142:143], v[250:251], 0, s[16:17]
	s_mov_b32 m0, s43
	s_nop 0
	global_load_lds_dwordx4 v[142:143], off
	s_waitcnt vmcnt(8)
	s_waitcnt lgkmcnt(0)
	s_barrier
; #define PG8_STAGE(bufoff, gbase, voff) do { _Pragma("unroll") for (int _i = 0; _i < 2; ++_i) \
;         __builtin_amdgcn_global_load_lds((const unsigned*)((const char*)(gbase) + (voff)[_i]), (PG8_LAS unsigned*)(lds + (bufoff) + ldsw + _i * 8192), 16, 0, 0); } while (0)
; #define PG8_LDA(dst, b, h) do { _Pragma("unroll") for (int m = 0; m < 4; ++m) _Pragma("unroll") for (int k = 0; k < 2; ++k) dst[m][k] = *(const PG8_LAS bf16x8*)(lds + PG8_SA(b, h) + aoff + m * 2048 + k * 1024); } while (0)
; #define PG8_LDB(dst, b, h) do { _Pragma("unroll") for (int n = 0; n < 2; ++n) _Pragma("unroll") for (int k = 0; k < 2; ++k) dst[n][k] = *(const PG8_LAS bf16x8*)(lds + PG8_SB(b, h) + boff + n * 2048 + k * 1024); } while (0)
; #define PG8_MMA(ai, bj, At, Bt) do { __builtin_amdgcn_s_setprio(1); _Pragma("unroll") for (int m = 0; m < 4; ++m) _Pragma("unroll") for (int n = 0; n < 2; ++n) _Pragma("unroll") for (int k = 0; k < 2; ++k) \
;         acc[ai][bj][m][n] = __builtin_amdgcn_mfma_f32_16x16x32_bf16(Bt[n][k], At[m][k], acc[ai][bj][m][n], 0, 0, 0); __builtin_amdgcn_s_setprio(0); } while (0)
; #define PG8_WAIT_V(n) asm volatile("s_waitcnt vmcnt(" #n ")" ::: "memory")
; #define PG8_WAIT_L(n) asm volatile("s_waitcnt lgkmcnt(" #n ")" ::: "memory")
; #define PG8_BAR __builtin_amdgcn_s_barrier()
; #define PG8_SCHED __builtin_amdgcn_sched_barrier(0)
; template <class Epi, class Sched, bool ALIGN_EPI = false, bool SP2 = false>
; __device__ __forceinline__ void gemm_phase(PG8_LAS unsigned char* lds, const Gemm g, const Sched& S, const Epi& E, int wave_s) {
;     ...
;             PG8_WAIT_V(8); PG8_WAIT_L(0); PG8_BAR; PG8_MMA(1, 0, At, B0); PG8_MMA(1, 1, At, B1); PG8_BAR; PG8_SCHED;
;             PG8_LDB(B0, 1, 0); PG8_LDB(B1, 1, 1); PG8_SCHED; PG8_LDA(At, 1, 0); PG8_STAGE(PG8_SA(0, 1), a2 + hstep, voffA);
;             PG8_WAIT_V(8); PG8_WAIT_L(0); PG8_BAR; PG8_MMA(0, 0, At, B0); PG8_MMA(0, 1, At, B1); PG8_BAR; PG8_SCHED;
	s_waitcnt lgkmcnt(0)
	v_mfma_f32_16x16x32_bf16 v[142:145], v[0:3], v[60:63], 0
	v_mfma_f32_16x16x32_bf16 v[156:159], v[0:3], v[92:95], 0
	v_mfma_f32_16x16x32_bf16 v[164:167], v[0:3], v[108:111], 0
	v_mfma_f32_16x16x32_bf16 v[0:3], v[0:3], v[120:123], 0
	v_mfma_f32_16x16x32_bf16 v[144:147], v[4:7], v[88:91], v[142:145]
	v_mfma_f32_16x16x32_bf16 v[156:159], v[4:7], v[104:107], v[156:159]
	v_mfma_f32_16x16x32_bf16 v[164:167], v[4:7], v[116:119], v[164:167]
	v_mfma_f32_16x16x32_bf16 v[0:3], v[4:7], v[124:127], v[0:3]
	v_mfma_f32_16x16x32_bf16 v[4:7], v[8:11], v[120:123], 0
	v_mfma_f32_16x16x32_bf16 v[152:155], v[8:11], v[60:63], 0
	v_mfma_f32_16x16x32_bf16 v[160:163], v[8:11], v[92:95], 0
	v_mfma_f32_16x16x32_bf16 v[168:171], v[8:11], v[108:111], 0
	v_mfma_f32_16x16x32_bf16 v[4:7], v[12:15], v[124:127], v[4:7]
	v_mfma_f32_16x16x32_bf16 v[152:155], v[12:15], v[88:91], v[152:155]
	v_mfma_f32_16x16x32_bf16 v[160:163], v[12:15], v[104:107], v[160:163]
	v_mfma_f32_16x16x32_bf16 v[168:171], v[12:15], v[116:119], v[168:171]
	v_mfma_f32_16x16x32_bf16 v[8:11], v[16:19], v[60:63], 0
	v_mfma_f32_16x16x32_bf16 v[172:175], v[20:23], v[88:91], v[8:11]
	v_mfma_f32_16x16x32_bf16 v[8:11], v[24:27], v[60:63], 0
	v_mfma_f32_16x16x32_bf16 v[176:179], v[28:31], v[88:91], v[8:11]
	v_mfma_f32_16x16x32_bf16 v[8:11], v[16:19], v[92:95], 0
	v_mfma_f32_16x16x32_bf16 v[180:183], v[20:23], v[104:107], v[8:11]
	v_mfma_f32_16x16x32_bf16 v[8:11], v[24:27], v[92:95], 0
	v_mfma_f32_16x16x32_bf16 v[184:187], v[28:31], v[104:107], v[8:11]
	v_mfma_f32_16x16x32_bf16 v[8:11], v[16:19], v[108:111], 0
	v_mfma_f32_16x16x32_bf16 v[188:191], v[20:23], v[116:119], v[8:11]
	v_mfma_f32_16x16x32_bf16 v[8:11], v[24:27], v[108:111], 0
	v_mfma_f32_16x16x32_bf16 v[192:195], v[28:31], v[116:119], v[8:11]
	v_mfma_f32_16x16x32_bf16 v[8:11], v[16:19], v[120:123], 0
	v_mfma_f32_16x16x32_bf16 v[196:199], v[20:23], v[124:127], v[8:11]
	v_mfma_f32_16x16x32_bf16 v[8:11], v[24:27], v[120:123], 0
	v_mfma_f32_16x16x32_bf16 v[200:203], v[28:31], v[124:127], v[8:11]
	s_barrier
	s_add_i32 s82, 0, 0x18000
	s_add_i32 s84, 0, 0x1c000
	v_add_u32_e32 v142, s82, v148
	v_add_u32_e32 v143, s84, v148
	s_nop 0
	ds_read_b128 v[8:11], v142
	ds_read_b128 v[12:15], v142 offset:1024
	ds_read_b128 v[16:19], v142 offset:2048
	ds_read_b128 v[20:23], v142 offset:3072
	ds_read_b128 v[204:207], v143
	ds_read_b128 v[208:211], v143 offset:1024
	ds_read_b128 v[212:215], v143 offset:2048
	ds_read_b128 v[216:219], v143 offset:3072
	s_add_u32 s48, s44, 0x100100
	s_addc_u32 s49, s45, 0
	s_mov_b32 m0, s58
	v_lshl_add_u64 v[88:89], s[48:49], 0, v[134:135]
	ds_read_b128 v[24:27], v151 offset:32768
	ds_read_b128 v[28:31], v151 offset:33792
	ds_read_b128 v[60:63], v151 offset:34816
	ds_read_b128 v[220:223], v151 offset:35840
	ds_read_b128 v[224:227], v151 offset:36864
	ds_read_b128 v[228:231], v151 offset:37888
	ds_read_b128 v[232:235], v151 offset:38912
	ds_read_b128 v[236:239], v151 offset:39936
	global_load_lds_dwordx4 v[88:89], off
	v_lshl_add_u64 v[88:89], s[48:49], 0, v[130:131]
	s_mov_b32 m0, s59
	s_nop 0
	global_load_lds_dwordx4 v[88:89], off
	s_waitcnt vmcnt(8)
	s_waitcnt lgkmcnt(0)
	s_barrier
	s_waitcnt lgkmcnt(0)
	v_mfma_f32_16x16x32_bf16 v[64:67], v[8:11], v[24:27], v[64:67]
	v_mfma_f32_16x16x32_bf16 v[124:127], v[12:15], v[28:31], v[64:67]
	v_mfma_f32_16x16x32_bf16 v[64:67], v[16:19], v[24:27], v[68:71]
	v_mfma_f32_16x16x32_bf16 v[120:123], v[20:23], v[28:31], v[64:67]
	v_mfma_f32_16x16x32_bf16 v[64:67], v[8:11], v[60:63], v[72:75]
	v_mfma_f32_16x16x32_bf16 v[108:111], v[12:15], v[220:223], v[64:67]
	v_mfma_f32_16x16x32_bf16 v[64:67], v[16:19], v[60:63], v[76:79]
	v_mfma_f32_16x16x32_bf16 v[104:107], v[20:23], v[220:223], v[64:67]
	v_mfma_f32_16x16x32_bf16 v[64:67], v[8:11], v[224:227], v[80:83]
	v_mfma_f32_16x16x32_bf16 v[92:95], v[12:15], v[228:231], v[64:67]
	v_mfma_f32_16x16x32_bf16 v[64:67], v[16:19], v[224:227], v[84:87]
	v_mfma_f32_16x16x32_bf16 v[88:91], v[20:23], v[228:231], v[64:67]
	v_mfma_f32_16x16x32_bf16 v[64:67], v[8:11], v[232:235], v[96:99]
	v_mfma_f32_16x16x32_bf16 v[76:79], v[12:15], v[236:239], v[64:67]
	v_mfma_f32_16x16x32_bf16 v[64:67], v[16:19], v[232:235], v[100:103]
	v_mfma_f32_16x16x32_bf16 v[72:75], v[20:23], v[236:239], v[64:67]
	v_mfma_f32_16x16x32_bf16 v[64:67], v[204:207], v[24:27], v[112:115]
	v_mfma_f32_16x16x32_bf16 v[24:27], v[212:215], v[24:27], v[32:35]
	v_mfma_f32_16x16x32_bf16 v[112:115], v[216:219], v[28:31], v[24:27]
	v_mfma_f32_16x16x32_bf16 v[24:27], v[204:207], v[60:63], v[36:39]
	v_mfma_f32_16x16x32_bf16 v[100:103], v[208:211], v[220:223], v[24:27]
	v_mfma_f32_16x16x32_bf16 v[24:27], v[212:215], v[60:63], v[40:43]
	v_mfma_f32_16x16x32_bf16 v[96:99], v[216:219], v[220:223], v[24:27]
	v_mfma_f32_16x16x32_bf16 v[24:27], v[204:207], v[224:227], v[44:47]
	v_mfma_f32_16x16x32_bf16 v[84:87], v[208:211], v[228:231], v[24:27]
	v_mfma_f32_16x16x32_bf16 v[24:27], v[212:215], v[224:227], v[48:51]
	v_mfma_f32_16x16x32_bf16 v[80:83], v[216:219], v[228:231], v[24:27]
	v_mfma_f32_16x16x32_bf16 v[24:27], v[204:207], v[232:235], v[52:55]
	v_mfma_f32_16x16x32_bf16 v[68:71], v[208:211], v[236:239], v[24:27]
	v_mfma_f32_16x16x32_bf16 v[24:27], v[212:215], v[232:235], v[56:59]
	v_mfma_f32_16x16x32_bf16 v[116:119], v[208:211], v[28:31], v[64:67]
	v_mfma_f32_16x16x32_bf16 v[64:67], v[216:219], v[236:239], v[24:27]
	s_barrier
; #define PG8_STAGE(bufoff, gbase, voff) do { _Pragma("unroll") for (int _i = 0; _i < 2; ++_i) \
;         __builtin_amdgcn_global_load_lds((const unsigned*)((const char*)(gbase) + (voff)[_i]), (PG8_LAS unsigned*)(lds + (bufoff) + ldsw + _i * 8192), 16, 0, 0); } while (0)
; #define PG8_LDA(dst, b, h) do { _Pragma("unroll") for (int m = 0; m < 4; ++m) _Pragma("unroll") for (int k = 0; k < 2; ++k) dst[m][k] = *(const PG8_LAS bf16x8*)(lds + PG8_SA(b, h) + aoff + m * 2048 + k * 1024); } while (0)
; #define PG8_MMA(ai, bj, At, Bt) do { __builtin_amdgcn_s_setprio(1); _Pragma("unroll") for (int m = 0; m < 4; ++m) _Pragma("unroll") for (int n = 0; n < 2; ++n) _Pragma("unroll") for (int k = 0; k < 2; ++k) \
;         acc[ai][bj][m][n] = __builtin_amdgcn_mfma_f32_16x16x32_bf16(Bt[n][k], At[m][k], acc[ai][bj][m][n], 0, 0, 0); __builtin_amdgcn_s_setprio(0); } while (0)
; #define PG8_WAIT_V(n) asm volatile("s_waitcnt vmcnt(" #n ")" ::: "memory")
; #define PG8_WAIT_L(n) asm volatile("s_waitcnt lgkmcnt(" #n ")" ::: "memory")
; #define PG8_BAR __builtin_amdgcn_s_barrier()
; #define PG8_SCHED __builtin_amdgcn_sched_barrier(0)
; template <class Epi, class Sched, bool ALIGN_EPI = false, bool SP2 = false>
; __device__ __forceinline__ void gemm_phase(PG8_LAS unsigned char* lds, const Gemm g, const Sched& S, const Epi& E, int wave_s) {
;     ...
;             PG8_LDA(At, 1, 1); PG8_STAGE(PG8_SB(1, 0), b3, voffB); PG8_STAGE(PG8_SB(1, 1), b3 + hstep, voffB); PG8_STAGE(PG8_SA(1, 0), a3, voffA);
;             PG8_WAIT_V(8); PG8_WAIT_L(0); PG8_BAR; PG8_MMA(1, 0, At, B0); PG8_MMA(1, 1, At, B1); PG8_BAR; PG8_SCHED;
	s_add_i32 s82, s82, s57
	s_add_i32 s83, s82, 0x2000
	s_nop 1
	v_lshl_add_u64 v[24:25], v[244:245], 0, s[18:19]
	s_mov_b32 m0, s82
	s_add_u32 s48, s46, 0x100180
	ds_read_b128 v[32:35], v151 offset:49152
	ds_read_b128 v[36:39], v151 offset:50176
	ds_read_b128 v[220:223], v151 offset:51200
	ds_read_b128 v[224:227], v151 offset:52224
	ds_read_b128 v[228:231], v151 offset:53248
	ds_read_b128 v[232:235], v151 offset:54272
	ds_read_b128 v[236:239], v151 offset:55296
	ds_read_b128 v[240:243], v151 offset:56320
	global_load_lds_dwordx4 v[24:25], off
	v_lshl_add_u64 v[24:25], v[246:247], 0, s[18:19]
	s_mov_b32 m0, s83
	s_addc_u32 s49, s47, 0
	s_add_i32 s84, s84, s57
	global_load_lds_dwordx4 v[24:25], off
	v_lshl_add_u64 v[24:25], s[48:49], 0, v[132:133]
	s_mov_b32 m0, s84
	s_add_i32 s85, s84, 0x2000
	global_load_lds_dwordx4 v[24:25], off
	v_lshl_add_u64 v[24:25], s[48:49], 0, v[128:129]
	s_mov_b32 m0, s85
	s_nop 0
	global_load_lds_dwordx4 v[24:25], off
	v_lshl_add_u64 v[24:25], v[248:249], 0, s[18:19]
	s_mov_b32 m0, s62
	s_nop 0
	global_load_lds_dwordx4 v[24:25], off
	v_lshl_add_u64 v[24:25], v[250:251], 0, s[18:19]
	s_mov_b32 m0, s63
	s_nop 0
	global_load_lds_dwordx4 v[24:25], off
	s_waitcnt vmcnt(8)
	s_waitcnt lgkmcnt(0)
	s_barrier
	s_waitcnt lgkmcnt(0)
	v_mfma_f32_16x16x32_bf16 v[24:27], v[8:11], v[32:35], v[144:147]
	v_mfma_f32_16x16x32_bf16 v[60:63], v[12:15], v[36:39], v[24:27]
	v_mfma_f32_16x16x32_bf16 v[24:27], v[16:19], v[32:35], v[152:155]
	v_mfma_f32_16x16x32_bf16 v[56:59], v[20:23], v[36:39], v[24:27]
	v_mfma_f32_16x16x32_bf16 v[24:27], v[8:11], v[220:223], v[156:159]
	v_mfma_f32_16x16x32_bf16 v[44:47], v[12:15], v[224:227], v[24:27]
	v_mfma_f32_16x16x32_bf16 v[24:27], v[16:19], v[220:223], v[160:163]
	v_mfma_f32_16x16x32_bf16 v[40:43], v[20:23], v[224:227], v[24:27]
	v_mfma_f32_16x16x32_bf16 v[24:27], v[8:11], v[228:231], v[164:167]
	v_mfma_f32_16x16x32_bf16 v[0:3], v[8:11], v[236:239], v[0:3]
	v_mfma_f32_16x16x32_bf16 v[28:31], v[12:15], v[232:235], v[24:27]
	v_mfma_f32_16x16x32_bf16 v[24:27], v[16:19], v[228:231], v[168:171]
	v_mfma_f32_16x16x32_bf16 v[12:15], v[12:15], v[240:243], v[0:3]
	v_mfma_f32_16x16x32_bf16 v[0:3], v[16:19], v[236:239], v[4:7]
	v_mfma_f32_16x16x32_bf16 v[24:27], v[20:23], v[232:235], v[24:27]
	v_mfma_f32_16x16x32_bf16 v[8:11], v[20:23], v[240:243], v[0:3]
	v_mfma_f32_16x16x32_bf16 v[0:3], v[204:207], v[32:35], v[172:175]
	v_mfma_f32_16x16x32_bf16 v[52:55], v[208:211], v[36:39], v[0:3]
	v_mfma_f32_16x16x32_bf16 v[0:3], v[212:215], v[32:35], v[176:179]
	v_mfma_f32_16x16x32_bf16 v[48:51], v[216:219], v[36:39], v[0:3]
	v_mfma_f32_16x16x32_bf16 v[0:3], v[204:207], v[220:223], v[180:183]
	v_mfma_f32_16x16x32_bf16 v[36:39], v[208:211], v[224:227], v[0:3]
	v_mfma_f32_16x16x32_bf16 v[0:3], v[212:215], v[220:223], v[184:187]
	v_mfma_f32_16x16x32_bf16 v[32:35], v[216:219], v[224:227], v[0:3]
	v_mfma_f32_16x16x32_bf16 v[0:3], v[204:207], v[228:231], v[188:191]
	v_mfma_f32_16x16x32_bf16 v[20:23], v[208:211], v[232:235], v[0:3]
	v_mfma_f32_16x16x32_bf16 v[0:3], v[212:215], v[228:231], v[192:195]
	v_mfma_f32_16x16x32_bf16 v[16:19], v[216:219], v[232:235], v[0:3]
	v_mfma_f32_16x16x32_bf16 v[0:3], v[204:207], v[236:239], v[196:199]
	v_mfma_f32_16x16x32_bf16 v[4:7], v[208:211], v[240:243], v[0:3]
	v_mfma_f32_16x16x32_bf16 v[0:3], v[212:215], v[236:239], v[200:203]
	v_mfma_f32_16x16x32_bf16 v[0:3], v[216:219], v[240:243], v[0:3]
	s_barrier
	s_add_u32 s44, s44, 0x100180
	s_addc_u32 s45, s45, 0
	s_add_u32 s86, s46, 0x200
	s_addc_u32 s87, s47, 0
	s_mov_b32 s88, 0
